# on the combination version: attention K/V offset increments as 32-bit adds; the scan's two remaining reduce-scatter lane masks computed once per scan instead of once per chunk
# speedup vs baseline: 1.0092x; 1.0092x over previous
; DI void phase_scan(const Params& p, char* smem) {
;     ...
;   const int tid = tid__, lane = tid & 63, wave = tid >> 6, kq = lane & 15, rg = lane >> 4;
;   const int chain = (blk & 7) + 8 * (blk >> 5), quarter = (blk >> 3) & 3;
;   const int b = chain >> 3, h = (chain >> 1) & 3, dir = chain & 1;
;   const u16* sc = (const u16*)(p.ws + OFF_R3);
;   const size_t AS = (size_t)NT * 256;
;   const u16* aOMW = sc + (dir ? SA_OMWB : SA_OMWF) * AS;
;   const u16* aKD = sc + (dir ? SA_KDB : SA_KDF) * AS;
;   const u16* aB = sc + (dir ? SA_BB : SA_BF) * AS;
;   const u16* aKKN = sc + SA_KKN * AS;
;   const u16* aR = sc + SA_R * AS;
;   const u16* aV = sc + SA_V * AS;
;   u16* Y = (u16*)(p.ws + OFF_R2) + (dir ? AS : 0);
;   constexpr int CH = 16, BSZ = 5 * CH * 64 + CH * 16;
;   float* buf = (float*)smem;
;   const int st_ld = tid >> 4, k4 = (tid & 15) * 4;
;   const int vrow = quarter * 16 + wave * 4 + rg;
;   uint2 g0, g1, g2, g3, g4; u16 gv;
;     ...
;   float2_t S01 = {0.f, 0.f}, S23 = {0.f, 0.f};
;   __builtin_amdgcn_s_setprio(3);
;   __syncthreads();
;   SCAN_GLOAD(0); SCAN_LSTORE(0);
;   __syncthreads();
;   constexpr int NCH = LK / CH;
.LBB0_506:
	s_or_b64 exec, exec, s[4:5]
	s_and_b64 s[4:5], s[0:1], exec
	s_cselect_b32 s4, s77, 0x8800000
	s_add_u32 s42, s22, s4
	s_addc_u32 s43, s23, 0
	s_mul_i32 s7, s7, 0x1100000
	s_add_u32 s4, s22, s7
	s_addc_u32 s5, s23, 0
	s_add_u32 s80, s4, 0x2200000
	s_addc_u32 s81, s5, 0
	s_and_b64 s[4:5], s[0:1], exec
	s_cselect_b32 s4, s3, 0x9900000
	s_add_u32 s40, s22, s4
	s_addc_u32 s41, s23, 0
	s_and_b64 s[4:5], s[0:1], exec
	s_cselect_b32 s4, 0, 0x1100000
	v_readlane_b32 s8, v254, 63
	v_readlane_b32 s9, v255, 0
	s_add_u32 s4, s8, s4
	s_addc_u32 s5, s9, 0
	s_lshl_b32 s7, s6, 1
	s_waitcnt vmcnt(0)
	v_ashrrev_i32_e32 v5, 31, v4
	s_lshl_b32 s6, s6, 5
	v_and_b32_e32 v18, 15, v14
	v_lshlrev_b64 v[20:21], 8, v[4:5]
	s_and_b32 s55, s6, 0xc0
	v_lshlrev_b32_e32 v2, 2, v18
	v_or_b32_e32 v20, s55, v20
	v_or_b32_e32 v4, v20, v2
	v_mov_b32_e32 v5, v21
	v_lshlrev_b64 v[12:13], 1, v[4:5]
	v_lshl_add_u64 v[4:5], s[42:43], 0, v[12:13]
	flat_load_dwordx2 v[4:5], v[4:5]
	v_lshl_add_u64 v[6:7], s[80:81], 0, v[12:13]
	v_readlane_b32 s8, v253, 39
	s_and_b32 s7, s7, 48
	v_and_b32_e32 v25, -4, v3
	flat_load_dwordx2 v[6:7], v[6:7]
	v_lshl_add_u64 v[8:9], s[40:41], 0, v[12:13]
	v_readlane_b32 s9, v253, 40
	v_bfe_u32 v24, v14, 4, 2
	v_add_u32_e32 v0, s7, v25
	flat_load_dwordx2 v[8:9], v[8:9]
	v_lshl_add_u64 v[10:11], s[8:9], 0, v[12:13]
	v_lshl_add_u64 v[20:21], v[20:21], 1, s[26:27]
	s_lshl_b32 s64, s7, 1
	v_or_b32_e32 v16, v0, v24
	flat_load_dwordx2 v[10:11], v[10:11]
	v_lshl_add_u64 v[12:13], s[22:23], 0, v[12:13]
	v_lshl_add_u64 v[20:21], v[20:21], 0, s[64:65]
	v_lshlrev_b32_e32 v0, 1, v18
	flat_load_dwordx2 v[12:13], v[12:13]
	v_lshl_add_u64 v[20:21], v[20:21], 0, v[0:1]
	flat_load_ushort v27, v[20:21]
	v_lshlrev_b32_e32 v15, 4, v18
	v_lshl_or_b32 v26, v3, 8, v15
	v_and_b32_e32 v14, 0x3ffffff0, v14
	s_add_u32 s6, s26, s64
	s_addc_u32 s7, s27, 0
	v_ashrrev_i32_e32 v17, 31, v16
	v_cmp_eq_u32_e64 s[38:39], 15, v18
	s_nop 0
	s_nop 0
	v_cmp_eq_u32_e64 s[12:13], 4, v18
	v_cmp_eq_u32_e64 s[14:15], 5, v18
	v_cmp_eq_u32_e64 s[16:17], 6, v18
	v_cmp_eq_u32_e64 s[18:19], 7, v18
	v_cmp_eq_u32_e64 s[20:21], 8, v18
	v_cmp_eq_u32_e64 s[22:23], 9, v18
	v_cmp_eq_u32_e64 s[24:25], 10, v18
	v_cmp_eq_u32_e64 s[26:27], 11, v18
	v_cmp_eq_u32_e64 s[28:29], 13, v18
	v_cmp_eq_u32_e64 s[34:35], 12, v18
	v_cmp_eq_u32_e64 s[36:37], 14, v18
	s_mov_b32 s54, 0
	s_mov_b32 s64, -16
	s_mov_b32 s96, 0
	v_and_b32_e32 v52, 8, v2
	v_and_b32_e32 v53, 4, v2
	v_cmp_ne_u32_e64 s[8:9], 0, v52
	v_cmp_ne_u32_e64 s[10:11], 0, v53
	s_waitcnt vmcnt(0) lgkmcnt(0)
	v_lshlrev_b32_e32 v20, 16, v4
	v_and_b32_e32 v21, 0xffff0000, v4
	v_pk_add_f32 v[28:29], v[20:21], 1.0 op_sel_hi:[1,0] neg_lo:[1,0] neg_hi:[1,0]
	v_lshlrev_b32_e32 v20, 16, v5
	v_and_b32_e32 v21, 0xffff0000, v5
	v_pk_add_f32 v[30:31], v[20:21], 1.0 op_sel_hi:[1,0] neg_lo:[1,0] neg_hi:[1,0]
	ds_write_b128 v26, v[28:31]
	v_lshlrev_b32_e32 v28, 16, v6
	v_and_b32_e32 v29, 0xffff0000, v6
	v_lshlrev_b32_e32 v30, 16, v7
	v_and_b32_e32 v31, 0xffff0000, v7
	ds_write_b128 v26, v[28:31] offset:4096
	v_lshlrev_b32_e32 v28, 16, v8
	v_and_b32_e32 v29, 0xffff0000, v8
	v_lshlrev_b32_e32 v30, 16, v9
	v_and_b32_e32 v31, 0xffff0000, v9
	ds_write_b128 v26, v[28:31] offset:8192
	v_lshlrev_b32_e32 v28, 16, v10
	v_and_b32_e32 v29, 0xffff0000, v10
	v_lshlrev_b32_e32 v30, 16, v11
	v_and_b32_e32 v31, 0xffff0000, v11
	ds_write_b128 v26, v[28:31] offset:12288
	v_lshlrev_b32_e32 v28, 16, v12
	v_and_b32_e32 v29, 0xffff0000, v12
	v_lshlrev_b32_e32 v30, 16, v13
	v_and_b32_e32 v31, 0xffff0000, v13
	ds_write_b128 v26, v[28:31] offset:16384
	v_lshlrev_b32_e32 v15, 16, v27
	v_lshl_or_b32 v28, v14, 2, v2
	ds_write_b32 v28, v15 offset:20480
	v_lshl_add_u64 v[14:15], s[6:7], 0, v[0:1]
	s_lshl_b32 s6, s55, 1
	s_add_u32 s4, s4, s6
	v_sub_u32_e32 v0, 0, v18
	s_addc_u32 s5, s5, 0
	v_cndmask_b32_e64 v0, v0, v18, s[0:1]
	v_lshl_add_u64 v[16:17], v[16:17], 1, s[4:5]
	v_cmp_eq_u32_e64 s[4:5], 0, v18
	v_cmp_eq_u32_e64 s[6:7], 1, v18
	v_mov_b32_e32 v18, 0
	v_sub_u32_e32 v29, 0, v3
	v_mov_b32_e32 v19, v18
	v_mov_b32_e32 v20, v18
	v_mov_b32_e32 v21, v18
	s_waitcnt lgkmcnt(0)
	s_barrier
	s_branch .LBB0_508

; DI void phase_scan(const Params& p, char* smem) {
;     ...
;     if (c + 1 < NCH) SCAN_GLOAD(c + 1);
;     const float* bb = buf + (c & 1) * BSZ;
;     const int rowbase = scan_row(b, dir, c * CH);
;     const int rstep = dir ? -1 : 1;
;     const float* bl = bb + kq * 4;
;     const float* bv = bb + 5 * CH * 64 + wave * 4 + rg;
;     float4 fwv[3], fkv[3], fbv[3], fav[3], frv[3]; float vvv[3];
; #pragma unroll
;     for (int q = 0; q < 2; ++q) {
;       fwv[q] = *(const float4*)(bl + 0 * CH * 64 + q * 64); fkv[q] = *(const float4*)(bl + 1 * CH * 64 + q * 64); fbv[q] = *(const float4*)(bl + 2 * CH * 64 + q * 64);
;       fav[q] = *(const float4*)(bl + 3 * CH * 64 + q * 64); frv[q] = *(const float4*)(bl + 4 * CH * 64 + q * 64); vvv[q] = bv[q * 16];
;     }
;     float ysel = 0.f, ypart = 0.f;
; #pragma unroll
;     for (int s = 0; s < CH; ++s) {
;       const float4 fw = fwv[s % 3], fk = fkv[s % 3], fb = fbv[s % 3], fa = fav[s % 3], fr = frv[s % 3];
;       const float vv = vvv[s % 3];
;       const float2_t a01 = {fa.x, fa.y}, a23 = {fa.z, fa.w};
;       const float2_t w01 = {fw.x, fw.y}, w23 = {fw.z, fw.w}, k01 = {fk.x, fk.y}, k23 = {fk.z, fk.w}, b01 = {fb.x, fb.y}, b23 = {fb.z, fb.w};
;       const float2_t r01 = {fr.x, fr.y}, r23 = {fr.z, fr.w};
;       const float2_t vv2 = {vv, vv};
;       if (s + 2 < CH) {
;         constexpr int dummy = 0; (void)dummy;
;         const int q = (s + 2) % 3;
;         fwv[q] = *(const float4*)(bl + 0 * CH * 64 + (s + 2) * 64); fkv[q] = *(const float4*)(bl + 1 * CH * 64 + (s + 2) * 64); fbv[q] = *(const float4*)(bl + 2 * CH * 64 + (s + 2) * 64);
;         fav[q] = *(const float4*)(bl + 3 * CH * 64 + (s + 2) * 64); frv[q] = *(const float4*)(bl + 4 * CH * 64 + (s + 2) * 64); vvv[q] = bv[(s + 2) * 16];
;       }
;       float2_t t2 = S01 * a01; t2 = S23 * a23 + t2;
;       const float2_t q01 = S01 * w01 + vv2 * k01, q23 = S23 * w23 + vv2 * k23;
;       float xs = t2.x + t2.y, ys = ypart;
;       xs += __builtin_bit_cast(float, __builtin_amdgcn_update_dpp(0, __builtin_bit_cast(int, xs), 0x128, 0xf, 0xf, false));
;       ys += __builtin_bit_cast(float, __builtin_amdgcn_update_dpp(0, __builtin_bit_cast(int, ys), 0x128, 0xf, 0xf, false));
;       xs += __builtin_bit_cast(float, __builtin_amdgcn_update_dpp(0, __builtin_bit_cast(int, xs), 0x124, 0xf, 0xf, false));
.LBB0_512:
	s_bitcmp1_b32 s96, 0
	s_cselect_b32 s79, 0x5400, 0
	v_lshlrev_b32_e32 v32, 2, v25
	v_lshlrev_b32_e32 v33, 2, v24
	v_add3_u32 v32, s79, v32, v33
	v_add_u32_e32 v32, 0x5000, v32
	v_lshl_or_b32 v31, v2, 2, s79
	ds_read2_b32 v[164:165], v32 offset0:0 offset1:16
	ds_read2_b32 v[166:167], v32 offset0:32 offset1:48
	ds_read2_b32 v[168:169], v32 offset0:64 offset1:80
	ds_read2_b32 v[170:171], v32 offset0:96 offset1:112
	ds_read_b128 v[100:103], v31 offset:0
	ds_read_b128 v[104:107], v31 offset:4096
	ds_read_b128 v[108:111], v31 offset:8192
	ds_read_b128 v[112:115], v31 offset:12288
	ds_read_b128 v[116:119], v31 offset:16384
	ds_read_b128 v[120:123], v31 offset:256
	ds_read_b128 v[124:127], v31 offset:4352
	ds_read_b128 v[128:131], v31 offset:8448
	ds_read_b128 v[132:135], v31 offset:12544
	ds_read_b128 v[136:139], v31 offset:16640
	v_add_u32_e32 v30, v30, v0
	s_add_i32 s96, s96, 1
	s_andn2_b64 vcc, exec, s[46:47]
	s_waitcnt lgkmcnt(5)
	v_pk_mul_f32 v[42:43], v[114:115], v[20:21]
	v_pk_mul_f32 v[46:47], v[102:103], v[20:21]
	v_pk_fma_f32 v[42:43], v[112:113], v[18:19], v[42:43]
	v_pk_mul_f32 v[44:45], v[100:101], v[18:19]
	v_add_f32_e32 v48, v42, v43
	v_pk_fma_f32 v[44:45], v[104:105], v[164:165], v[44:45] op_sel_hi:[1,0,1]
	v_pk_fma_f32 v[46:47], v[106:107], v[164:165], v[46:47] op_sel_hi:[1,0,1]
	v_add_f32_dpp v48, v48, v48 row_ror:8 row_mask:0xf bank_mask:0xf bound_ctrl:1
	ds_read_b128 v[140:143], v31 offset:512
	ds_read_b128 v[144:147], v31 offset:4608
	v_add_f32_dpp v48, v48, v48 row_ror:4 row_mask:0xf bank_mask:0xf bound_ctrl:1
	ds_read_b128 v[148:151], v31 offset:8704
	ds_read_b128 v[152:155], v31 offset:12800
	v_add_f32_dpp v48, v48, v48 row_ror:2 row_mask:0xf bank_mask:0xf bound_ctrl:1
	ds_read_b128 v[156:159], v31 offset:16896
	s_nop 0
	v_add_f32_dpp v48, v48, v48 row_ror:1 row_mask:0xf bank_mask:0xf bound_ctrl:1
	v_pk_fma_f32 v[18:19], v[108:109], v[48:49], v[44:45] op_sel_hi:[1,0,1]
	v_pk_fma_f32 v[20:21], v[110:111], v[48:49], v[46:47] op_sel_hi:[1,0,1]
	s_waitcnt lgkmcnt(5)
	v_pk_mul_f32 v[42:43], v[134:135], v[20:21]
	v_pk_mul_f32 v[46:47], v[122:123], v[20:21]
	v_pk_fma_f32 v[42:43], v[132:133], v[18:19], v[42:43]
	v_pk_mul_f32 v[44:45], v[120:121], v[18:19]
	v_add_f32_e32 v48, v42, v43
	v_pk_fma_f32 v[44:45], v[124:125], v[164:165], v[44:45] op_sel:[0,1,0]
	v_pk_fma_f32 v[46:47], v[126:127], v[164:165], v[46:47] op_sel:[0,1,0]
	v_add_f32_dpp v48, v48, v48 row_ror:8 row_mask:0xf bank_mask:0xf bound_ctrl:1
	v_pk_mul_f32 v[50:51], v[116:117], v[18:19]
	v_pk_fma_f32 v[50:51], v[118:119], v[20:21], v[50:51]
	v_add_f32_dpp v48, v48, v48 row_ror:4 row_mask:0xf bank_mask:0xf bound_ctrl:1
	v_add_f32_e32 v180, v50, v51
	ds_read_b128 v[100:103], v31 offset:768
	v_add_f32_dpp v48, v48, v48 row_ror:2 row_mask:0xf bank_mask:0xf bound_ctrl:1
	ds_read_b128 v[104:107], v31 offset:4864
	ds_read_b128 v[108:111], v31 offset:8960
	v_add_f32_dpp v48, v48, v48 row_ror:1 row_mask:0xf bank_mask:0xf bound_ctrl:1
	ds_read_b128 v[112:115], v31 offset:13056
	ds_read_b128 v[116:119], v31 offset:17152
	v_pk_fma_f32 v[18:19], v[128:129], v[48:49], v[44:45] op_sel_hi:[1,0,1]
	v_pk_fma_f32 v[20:21], v[130:131], v[48:49], v[46:47] op_sel_hi:[1,0,1]
	s_waitcnt lgkmcnt(5)
	v_pk_mul_f32 v[42:43], v[154:155], v[20:21]
	v_pk_mul_f32 v[46:47], v[142:143], v[20:21]
	v_pk_fma_f32 v[42:43], v[152:153], v[18:19], v[42:43]
	v_pk_mul_f32 v[44:45], v[140:141], v[18:19]
	v_add_f32_e32 v48, v42, v43
	v_pk_fma_f32 v[44:45], v[144:145], v[166:167], v[44:45] op_sel_hi:[1,0,1]
	v_pk_fma_f32 v[46:47], v[146:147], v[166:167], v[46:47] op_sel_hi:[1,0,1]
	v_add_f32_dpp v48, v48, v48 row_ror:8 row_mask:0xf bank_mask:0xf bound_ctrl:1
	v_pk_mul_f32 v[50:51], v[136:137], v[18:19]
	v_pk_fma_f32 v[50:51], v[138:139], v[20:21], v[50:51]
	v_add_f32_dpp v48, v48, v48 row_ror:4 row_mask:0xf bank_mask:0xf bound_ctrl:1
	v_add_f32_e32 v181, v50, v51
	ds_read_b128 v[120:123], v31 offset:1024
	v_add_f32_dpp v48, v48, v48 row_ror:2 row_mask:0xf bank_mask:0xf bound_ctrl:1
	ds_read_b128 v[124:127], v31 offset:5120
	ds_read_b128 v[128:131], v31 offset:9216
	v_add_f32_dpp v48, v48, v48 row_ror:1 row_mask:0xf bank_mask:0xf bound_ctrl:1
	ds_read_b128 v[132:135], v31 offset:13312
	ds_read_b128 v[136:139], v31 offset:17408
	ds_read2_b32 v[172:173], v32 offset0:128 offset1:144
	ds_read2_b32 v[174:175], v32 offset0:160 offset1:176
	v_pk_fma_f32 v[18:19], v[148:149], v[48:49], v[44:45] op_sel_hi:[1,0,1]
	v_pk_fma_f32 v[20:21], v[150:151], v[48:49], v[46:47] op_sel_hi:[1,0,1]
	s_waitcnt lgkmcnt(7)
	v_pk_mul_f32 v[42:43], v[114:115], v[20:21]
	v_pk_mul_f32 v[46:47], v[102:103], v[20:21]
	v_pk_fma_f32 v[42:43], v[112:113], v[18:19], v[42:43]
	v_pk_mul_f32 v[44:45], v[100:101], v[18:19]
	v_add_f32_e32 v48, v42, v43
	v_pk_fma_f32 v[44:45], v[104:105], v[166:167], v[44:45] op_sel:[0,1,0]
	v_pk_fma_f32 v[46:47], v[106:107], v[166:167], v[46:47] op_sel:[0,1,0]
	v_add_f32_dpp v48, v48, v48 row_ror:8 row_mask:0xf bank_mask:0xf bound_ctrl:1
	v_pk_mul_f32 v[50:51], v[156:157], v[18:19]
	v_pk_fma_f32 v[50:51], v[158:159], v[20:21], v[50:51]
	v_add_f32_dpp v48, v48, v48 row_ror:4 row_mask:0xf bank_mask:0xf bound_ctrl:1
	v_add_f32_e32 v182, v50, v51
	ds_read_b128 v[140:143], v31 offset:1280
	v_add_f32_dpp v48, v48, v48 row_ror:2 row_mask:0xf bank_mask:0xf bound_ctrl:1
	ds_read_b128 v[144:147], v31 offset:5376
	ds_read_b128 v[148:151], v31 offset:9472
	v_add_f32_dpp v48, v48, v48 row_ror:1 row_mask:0xf bank_mask:0xf bound_ctrl:1
	ds_read_b128 v[152:155], v31 offset:13568
	ds_read_b128 v[156:159], v31 offset:17664
	ds_read2_b32 v[176:177], v32 offset0:192 offset1:208
	ds_read2_b32 v[178:179], v32 offset0:224 offset1:240
	v_pk_fma_f32 v[18:19], v[108:109], v[48:49], v[44:45] op_sel_hi:[1,0,1]
	v_pk_fma_f32 v[20:21], v[110:111], v[48:49], v[46:47] op_sel_hi:[1,0,1]
	s_waitcnt lgkmcnt(9)
; DI void phase_scan(const Params& p, char* smem) {
;     ...
;     for (int s = 0; s < CH; ++s) {
;       const float4 fw = fwv[s % 3], fk = fkv[s % 3], fb = fbv[s % 3], fa = fav[s % 3], fr = frv[s % 3];
;       const float vv = vvv[s % 3];
;       const float2_t a01 = {fa.x, fa.y}, a23 = {fa.z, fa.w};
;       const float2_t w01 = {fw.x, fw.y}, w23 = {fw.z, fw.w}, k01 = {fk.x, fk.y}, k23 = {fk.z, fk.w}, b01 = {fb.x, fb.y}, b23 = {fb.z, fb.w};
;       const float2_t r01 = {fr.x, fr.y}, r23 = {fr.z, fr.w};
;       const float2_t vv2 = {vv, vv};
;       if (s + 2 < CH) {
;         constexpr int dummy = 0; (void)dummy;
;         const int q = (s + 2) % 3;
;         fwv[q] = *(const float4*)(bl + 0 * CH * 64 + (s + 2) * 64); fkv[q] = *(const float4*)(bl + 1 * CH * 64 + (s + 2) * 64); fbv[q] = *(const float4*)(bl + 2 * CH * 64 + (s + 2) * 64);
;         fav[q] = *(const float4*)(bl + 3 * CH * 64 + (s + 2) * 64); frv[q] = *(const float4*)(bl + 4 * CH * 64 + (s + 2) * 64); vvv[q] = bv[(s + 2) * 16];
;       }
;       float2_t t2 = S01 * a01; t2 = S23 * a23 + t2;
;       const float2_t q01 = S01 * w01 + vv2 * k01, q23 = S23 * w23 + vv2 * k23;
;       float xs = t2.x + t2.y, ys = ypart;
;       xs += __builtin_bit_cast(float, __builtin_amdgcn_update_dpp(0, __builtin_bit_cast(int, xs), 0x128, 0xf, 0xf, false));
;       ys += __builtin_bit_cast(float, __builtin_amdgcn_update_dpp(0, __builtin_bit_cast(int, ys), 0x128, 0xf, 0xf, false));
;       xs += __builtin_bit_cast(float, __builtin_amdgcn_update_dpp(0, __builtin_bit_cast(int, xs), 0x124, 0xf, 0xf, false));
;       ys += __builtin_bit_cast(float, __builtin_amdgcn_update_dpp(0, __builtin_bit_cast(int, ys), 0x124, 0xf, 0xf, false));
;       xs += __builtin_bit_cast(float, __builtin_amdgcn_update_dpp(0, __builtin_bit_cast(int, xs), 0x122, 0xf, 0xf, false));
;       ys += __builtin_bit_cast(float, __builtin_amdgcn_update_dpp(0, __builtin_bit_cast(int, ys), 0x122, 0xf, 0xf, false));
;       xs += __builtin_bit_cast(float, __builtin_amdgcn_update_dpp(0, __builtin_bit_cast(int, xs), 0x121, 0xf, 0xf, false));
;       ys += __builtin_bit_cast(float, __builtin_amdgcn_update_dpp(0, __builtin_bit_cast(int, ys), 0x121, 0xf, 0xf, false));
;       if (s > 0) ysel = (kq == s - 1) ? ys : ysel;
;       const float2_t sa2 = {xs, xs};
;       S01 = sa2 * b01 + q01; S23 = sa2 * b23 + q23;
;       float2_t y2 = S01 * r01; y2 = S23 * r23 + y2;
	v_pk_mul_f32 v[42:43], v[134:135], v[20:21]
	v_pk_mul_f32 v[46:47], v[122:123], v[20:21]
	v_pk_fma_f32 v[42:43], v[132:133], v[18:19], v[42:43]
	v_pk_mul_f32 v[44:45], v[120:121], v[18:19]
	v_add_f32_e32 v48, v42, v43
	v_pk_fma_f32 v[44:45], v[124:125], v[168:169], v[44:45] op_sel_hi:[1,0,1]
	v_pk_fma_f32 v[46:47], v[126:127], v[168:169], v[46:47] op_sel_hi:[1,0,1]
	v_add_f32_dpp v48, v48, v48 row_ror:8 row_mask:0xf bank_mask:0xf bound_ctrl:1
	v_pk_mul_f32 v[50:51], v[116:117], v[18:19]
	v_pk_fma_f32 v[50:51], v[118:119], v[20:21], v[50:51]
	v_add_f32_dpp v48, v48, v48 row_ror:4 row_mask:0xf bank_mask:0xf bound_ctrl:1
	v_add_f32_e32 v183, v50, v51
	ds_read_b128 v[100:103], v31 offset:1536
	v_add_f32_dpp v48, v48, v48 row_ror:2 row_mask:0xf bank_mask:0xf bound_ctrl:1
	ds_read_b128 v[104:107], v31 offset:5632
	ds_read_b128 v[108:111], v31 offset:9728
	v_add_f32_dpp v48, v48, v48 row_ror:1 row_mask:0xf bank_mask:0xf bound_ctrl:1
	ds_read_b128 v[112:115], v31 offset:13824
	ds_read_b128 v[116:119], v31 offset:17920
	v_pk_fma_f32 v[18:19], v[128:129], v[48:49], v[44:45] op_sel_hi:[1,0,1]
	v_pk_fma_f32 v[20:21], v[130:131], v[48:49], v[46:47] op_sel_hi:[1,0,1]
	s_waitcnt lgkmcnt(7)
	v_pk_mul_f32 v[42:43], v[154:155], v[20:21]
	v_pk_mul_f32 v[46:47], v[142:143], v[20:21]
	v_pk_fma_f32 v[42:43], v[152:153], v[18:19], v[42:43]
	v_pk_mul_f32 v[44:45], v[140:141], v[18:19]
	v_add_f32_e32 v48, v42, v43
	v_pk_fma_f32 v[44:45], v[144:145], v[168:169], v[44:45] op_sel:[0,1,0]
	v_pk_fma_f32 v[46:47], v[146:147], v[168:169], v[46:47] op_sel:[0,1,0]
	v_add_f32_dpp v48, v48, v48 row_ror:8 row_mask:0xf bank_mask:0xf bound_ctrl:1
	v_pk_mul_f32 v[50:51], v[136:137], v[18:19]
	v_pk_fma_f32 v[50:51], v[138:139], v[20:21], v[50:51]
	v_add_f32_dpp v48, v48, v48 row_ror:4 row_mask:0xf bank_mask:0xf bound_ctrl:1
	v_add_f32_e32 v184, v50, v51
	ds_read_b128 v[120:123], v31 offset:1792
	v_add_f32_dpp v48, v48, v48 row_ror:2 row_mask:0xf bank_mask:0xf bound_ctrl:1
	ds_read_b128 v[124:127], v31 offset:5888
	ds_read_b128 v[128:131], v31 offset:9984
	v_add_f32_dpp v48, v48, v48 row_ror:1 row_mask:0xf bank_mask:0xf bound_ctrl:1
	ds_read_b128 v[132:135], v31 offset:14080
	ds_read_b128 v[136:139], v31 offset:18176
	v_pk_fma_f32 v[18:19], v[148:149], v[48:49], v[44:45] op_sel_hi:[1,0,1]
	v_pk_fma_f32 v[20:21], v[150:151], v[48:49], v[46:47] op_sel_hi:[1,0,1]
	s_waitcnt lgkmcnt(5)
	v_pk_mul_f32 v[42:43], v[114:115], v[20:21]
	v_pk_mul_f32 v[46:47], v[102:103], v[20:21]
	v_pk_fma_f32 v[42:43], v[112:113], v[18:19], v[42:43]
	v_pk_mul_f32 v[44:45], v[100:101], v[18:19]
	v_add_f32_e32 v48, v42, v43
	v_pk_fma_f32 v[44:45], v[104:105], v[170:171], v[44:45] op_sel_hi:[1,0,1]
	v_pk_fma_f32 v[46:47], v[106:107], v[170:171], v[46:47] op_sel_hi:[1,0,1]
	v_add_f32_dpp v48, v48, v48 row_ror:8 row_mask:0xf bank_mask:0xf bound_ctrl:1
	v_pk_mul_f32 v[50:51], v[156:157], v[18:19]
	v_pk_fma_f32 v[50:51], v[158:159], v[20:21], v[50:51]
	v_add_f32_dpp v48, v48, v48 row_ror:4 row_mask:0xf bank_mask:0xf bound_ctrl:1
	v_add_f32_e32 v185, v50, v51
	ds_read_b128 v[140:143], v31 offset:2048
	v_add_f32_dpp v48, v48, v48 row_ror:2 row_mask:0xf bank_mask:0xf bound_ctrl:1
	ds_read_b128 v[144:147], v31 offset:6144
	ds_read_b128 v[148:151], v31 offset:10240
	v_add_f32_dpp v48, v48, v48 row_ror:1 row_mask:0xf bank_mask:0xf bound_ctrl:1
	ds_read_b128 v[152:155], v31 offset:14336
	ds_read_b128 v[156:159], v31 offset:18432
	v_pk_fma_f32 v[18:19], v[108:109], v[48:49], v[44:45] op_sel_hi:[1,0,1]
	v_pk_fma_f32 v[20:21], v[110:111], v[48:49], v[46:47] op_sel_hi:[1,0,1]
	s_waitcnt lgkmcnt(5)
	v_pk_mul_f32 v[42:43], v[134:135], v[20:21]
	v_pk_mul_f32 v[46:47], v[122:123], v[20:21]
	v_pk_fma_f32 v[42:43], v[132:133], v[18:19], v[42:43]
	v_pk_mul_f32 v[44:45], v[120:121], v[18:19]
	v_add_f32_e32 v48, v42, v43
	v_pk_fma_f32 v[44:45], v[124:125], v[170:171], v[44:45] op_sel:[0,1,0]
	v_pk_fma_f32 v[46:47], v[126:127], v[170:171], v[46:47] op_sel:[0,1,0]
	v_add_f32_dpp v48, v48, v48 row_ror:8 row_mask:0xf bank_mask:0xf bound_ctrl:1
	v_pk_mul_f32 v[50:51], v[116:117], v[18:19]
	v_pk_fma_f32 v[50:51], v[118:119], v[20:21], v[50:51]
	v_add_f32_dpp v48, v48, v48 row_ror:4 row_mask:0xf bank_mask:0xf bound_ctrl:1
	v_add_f32_e32 v186, v50, v51
	ds_read_b128 v[100:103], v31 offset:2304
	v_add_f32_dpp v48, v48, v48 row_ror:2 row_mask:0xf bank_mask:0xf bound_ctrl:1
	ds_read_b128 v[104:107], v31 offset:6400
	ds_read_b128 v[108:111], v31 offset:10496
	v_add_f32_dpp v48, v48, v48 row_ror:1 row_mask:0xf bank_mask:0xf bound_ctrl:1
	ds_read_b128 v[112:115], v31 offset:14592
	ds_read_b128 v[116:119], v31 offset:18688
	v_pk_fma_f32 v[18:19], v[128:129], v[48:49], v[44:45] op_sel_hi:[1,0,1]
	v_pk_fma_f32 v[20:21], v[130:131], v[48:49], v[46:47] op_sel_hi:[1,0,1]
	s_waitcnt lgkmcnt(5)
	v_pk_mul_f32 v[42:43], v[154:155], v[20:21]
	v_pk_mul_f32 v[46:47], v[142:143], v[20:21]
	v_pk_fma_f32 v[42:43], v[152:153], v[18:19], v[42:43]
	v_pk_mul_f32 v[44:45], v[140:141], v[18:19]
	v_add_f32_e32 v48, v42, v43
	v_pk_fma_f32 v[44:45], v[144:145], v[172:173], v[44:45] op_sel_hi:[1,0,1]
	v_pk_fma_f32 v[46:47], v[146:147], v[172:173], v[46:47] op_sel_hi:[1,0,1]
	v_add_f32_dpp v48, v48, v48 row_ror:8 row_mask:0xf bank_mask:0xf bound_ctrl:1
	v_pk_mul_f32 v[50:51], v[136:137], v[18:19]
	v_pk_fma_f32 v[50:51], v[138:139], v[20:21], v[50:51]
	v_add_f32_dpp v48, v48, v48 row_ror:4 row_mask:0xf bank_mask:0xf bound_ctrl:1
	v_add_f32_e32 v187, v50, v51
	ds_read_b128 v[120:123], v31 offset:2560
	v_add_f32_dpp v48, v48, v48 row_ror:2 row_mask:0xf bank_mask:0xf bound_ctrl:1
	ds_read_b128 v[124:127], v31 offset:6656
	ds_read_b128 v[128:131], v31 offset:10752
	v_add_f32_dpp v48, v48, v48 row_ror:1 row_mask:0xf bank_mask:0xf bound_ctrl:1
	ds_read_b128 v[132:135], v31 offset:14848
	ds_read_b128 v[136:139], v31 offset:18944
	v_pk_fma_f32 v[18:19], v[148:149], v[48:49], v[44:45] op_sel_hi:[1,0,1]
	v_pk_fma_f32 v[20:21], v[150:151], v[48:49], v[46:47] op_sel_hi:[1,0,1]
	s_waitcnt lgkmcnt(5)
; DI void phase_scan(const Params& p, char* smem) {
;     ...
;     for (int s = 0; s < CH; ++s) {
;       const float4 fw = fwv[s % 3], fk = fkv[s % 3], fb = fbv[s % 3], fa = fav[s % 3], fr = frv[s % 3];
;       const float vv = vvv[s % 3];
;       const float2_t a01 = {fa.x, fa.y}, a23 = {fa.z, fa.w};
;       const float2_t w01 = {fw.x, fw.y}, w23 = {fw.z, fw.w}, k01 = {fk.x, fk.y}, k23 = {fk.z, fk.w}, b01 = {fb.x, fb.y}, b23 = {fb.z, fb.w};
;       const float2_t r01 = {fr.x, fr.y}, r23 = {fr.z, fr.w};
;       const float2_t vv2 = {vv, vv};
;       if (s + 2 < CH) {
;         constexpr int dummy = 0; (void)dummy;
;         const int q = (s + 2) % 3;
;         fwv[q] = *(const float4*)(bl + 0 * CH * 64 + (s + 2) * 64); fkv[q] = *(const float4*)(bl + 1 * CH * 64 + (s + 2) * 64); fbv[q] = *(const float4*)(bl + 2 * CH * 64 + (s + 2) * 64);
;         fav[q] = *(const float4*)(bl + 3 * CH * 64 + (s + 2) * 64); frv[q] = *(const float4*)(bl + 4 * CH * 64 + (s + 2) * 64); vvv[q] = bv[(s + 2) * 16];
;       }
;       float2_t t2 = S01 * a01; t2 = S23 * a23 + t2;
;       const float2_t q01 = S01 * w01 + vv2 * k01, q23 = S23 * w23 + vv2 * k23;
;       float xs = t2.x + t2.y, ys = ypart;
;       xs += __builtin_bit_cast(float, __builtin_amdgcn_update_dpp(0, __builtin_bit_cast(int, xs), 0x128, 0xf, 0xf, false));
;       ys += __builtin_bit_cast(float, __builtin_amdgcn_update_dpp(0, __builtin_bit_cast(int, ys), 0x128, 0xf, 0xf, false));
;       xs += __builtin_bit_cast(float, __builtin_amdgcn_update_dpp(0, __builtin_bit_cast(int, xs), 0x124, 0xf, 0xf, false));
;       ys += __builtin_bit_cast(float, __builtin_amdgcn_update_dpp(0, __builtin_bit_cast(int, ys), 0x124, 0xf, 0xf, false));
;       xs += __builtin_bit_cast(float, __builtin_amdgcn_update_dpp(0, __builtin_bit_cast(int, xs), 0x122, 0xf, 0xf, false));
;       ys += __builtin_bit_cast(float, __builtin_amdgcn_update_dpp(0, __builtin_bit_cast(int, ys), 0x122, 0xf, 0xf, false));
;       xs += __builtin_bit_cast(float, __builtin_amdgcn_update_dpp(0, __builtin_bit_cast(int, xs), 0x121, 0xf, 0xf, false));
;       ys += __builtin_bit_cast(float, __builtin_amdgcn_update_dpp(0, __builtin_bit_cast(int, ys), 0x121, 0xf, 0xf, false));
;       if (s > 0) ysel = (kq == s - 1) ? ys : ysel;
;       const float2_t sa2 = {xs, xs};
;       S01 = sa2 * b01 + q01; S23 = sa2 * b23 + q23;
;       float2_t y2 = S01 * r01; y2 = S23 * r23 + y2;
	v_pk_mul_f32 v[42:43], v[114:115], v[20:21]
	v_pk_mul_f32 v[46:47], v[102:103], v[20:21]
	v_pk_fma_f32 v[42:43], v[112:113], v[18:19], v[42:43]
	v_pk_mul_f32 v[44:45], v[100:101], v[18:19]
	v_add_f32_e32 v48, v42, v43
	v_pk_fma_f32 v[44:45], v[104:105], v[172:173], v[44:45] op_sel:[0,1,0]
	v_pk_fma_f32 v[46:47], v[106:107], v[172:173], v[46:47] op_sel:[0,1,0]
	v_add_f32_dpp v48, v48, v48 row_ror:8 row_mask:0xf bank_mask:0xf bound_ctrl:1
	v_pk_mul_f32 v[50:51], v[156:157], v[18:19]
	v_pk_fma_f32 v[50:51], v[158:159], v[20:21], v[50:51]
	v_add_f32_dpp v48, v48, v48 row_ror:4 row_mask:0xf bank_mask:0xf bound_ctrl:1
	v_add_f32_e32 v188, v50, v51
	ds_read_b128 v[140:143], v31 offset:2816
	v_add_f32_dpp v48, v48, v48 row_ror:2 row_mask:0xf bank_mask:0xf bound_ctrl:1
	ds_read_b128 v[144:147], v31 offset:6912
	ds_read_b128 v[148:151], v31 offset:11008
	v_add_f32_dpp v48, v48, v48 row_ror:1 row_mask:0xf bank_mask:0xf bound_ctrl:1
	ds_read_b128 v[152:155], v31 offset:15104
	ds_read_b128 v[156:159], v31 offset:19200
	v_pk_fma_f32 v[18:19], v[108:109], v[48:49], v[44:45] op_sel_hi:[1,0,1]
	v_pk_fma_f32 v[20:21], v[110:111], v[48:49], v[46:47] op_sel_hi:[1,0,1]
	s_waitcnt lgkmcnt(5)
	v_pk_mul_f32 v[42:43], v[134:135], v[20:21]
	v_pk_mul_f32 v[46:47], v[122:123], v[20:21]
	v_pk_fma_f32 v[42:43], v[132:133], v[18:19], v[42:43]
	v_pk_mul_f32 v[44:45], v[120:121], v[18:19]
	v_add_f32_e32 v48, v42, v43
	v_pk_fma_f32 v[44:45], v[124:125], v[174:175], v[44:45] op_sel_hi:[1,0,1]
	v_pk_fma_f32 v[46:47], v[126:127], v[174:175], v[46:47] op_sel_hi:[1,0,1]
	v_add_f32_dpp v48, v48, v48 row_ror:8 row_mask:0xf bank_mask:0xf bound_ctrl:1
	v_pk_mul_f32 v[50:51], v[116:117], v[18:19]
	v_pk_fma_f32 v[50:51], v[118:119], v[20:21], v[50:51]
	v_add_f32_dpp v48, v48, v48 row_ror:4 row_mask:0xf bank_mask:0xf bound_ctrl:1
	v_add_f32_e32 v189, v50, v51
	ds_read_b128 v[100:103], v31 offset:3072
	v_add_f32_dpp v48, v48, v48 row_ror:2 row_mask:0xf bank_mask:0xf bound_ctrl:1
	ds_read_b128 v[104:107], v31 offset:7168
	ds_read_b128 v[108:111], v31 offset:11264
	v_add_f32_dpp v48, v48, v48 row_ror:1 row_mask:0xf bank_mask:0xf bound_ctrl:1
	ds_read_b128 v[112:115], v31 offset:15360
	ds_read_b128 v[116:119], v31 offset:19456
	v_pk_fma_f32 v[18:19], v[128:129], v[48:49], v[44:45] op_sel_hi:[1,0,1]
	v_pk_fma_f32 v[20:21], v[130:131], v[48:49], v[46:47] op_sel_hi:[1,0,1]
	s_waitcnt lgkmcnt(5)
	v_pk_mul_f32 v[42:43], v[154:155], v[20:21]
	v_pk_mul_f32 v[46:47], v[142:143], v[20:21]
	v_pk_fma_f32 v[42:43], v[152:153], v[18:19], v[42:43]
	v_pk_mul_f32 v[44:45], v[140:141], v[18:19]
	v_add_f32_e32 v48, v42, v43
	v_pk_fma_f32 v[44:45], v[144:145], v[174:175], v[44:45] op_sel:[0,1,0]
	v_pk_fma_f32 v[46:47], v[146:147], v[174:175], v[46:47] op_sel:[0,1,0]
	v_add_f32_dpp v48, v48, v48 row_ror:8 row_mask:0xf bank_mask:0xf bound_ctrl:1
	v_pk_mul_f32 v[50:51], v[136:137], v[18:19]
	v_pk_fma_f32 v[50:51], v[138:139], v[20:21], v[50:51]
	v_add_f32_dpp v48, v48, v48 row_ror:4 row_mask:0xf bank_mask:0xf bound_ctrl:1
	v_add_f32_e32 v190, v50, v51
	ds_read_b128 v[120:123], v31 offset:3328
	v_add_f32_dpp v48, v48, v48 row_ror:2 row_mask:0xf bank_mask:0xf bound_ctrl:1
	ds_read_b128 v[124:127], v31 offset:7424
	ds_read_b128 v[128:131], v31 offset:11520
	v_add_f32_dpp v48, v48, v48 row_ror:1 row_mask:0xf bank_mask:0xf bound_ctrl:1
	ds_read_b128 v[132:135], v31 offset:15616
	ds_read_b128 v[136:139], v31 offset:19712
	v_pk_fma_f32 v[18:19], v[148:149], v[48:49], v[44:45] op_sel_hi:[1,0,1]
	v_pk_fma_f32 v[20:21], v[150:151], v[48:49], v[46:47] op_sel_hi:[1,0,1]
	s_waitcnt lgkmcnt(5)
	v_pk_mul_f32 v[42:43], v[114:115], v[20:21]
	v_pk_mul_f32 v[46:47], v[102:103], v[20:21]
	v_pk_fma_f32 v[42:43], v[112:113], v[18:19], v[42:43]
	v_pk_mul_f32 v[44:45], v[100:101], v[18:19]
	v_add_f32_e32 v48, v42, v43
	v_pk_fma_f32 v[44:45], v[104:105], v[176:177], v[44:45] op_sel_hi:[1,0,1]
	v_pk_fma_f32 v[46:47], v[106:107], v[176:177], v[46:47] op_sel_hi:[1,0,1]
	v_add_f32_dpp v48, v48, v48 row_ror:8 row_mask:0xf bank_mask:0xf bound_ctrl:1
	v_pk_mul_f32 v[50:51], v[156:157], v[18:19]
	v_pk_fma_f32 v[50:51], v[158:159], v[20:21], v[50:51]
	v_add_f32_dpp v48, v48, v48 row_ror:4 row_mask:0xf bank_mask:0xf bound_ctrl:1
	v_add_f32_e32 v191, v50, v51
	ds_read_b128 v[140:143], v31 offset:3584
	v_add_f32_dpp v48, v48, v48 row_ror:2 row_mask:0xf bank_mask:0xf bound_ctrl:1
	ds_read_b128 v[144:147], v31 offset:7680
	ds_read_b128 v[148:151], v31 offset:11776
	v_add_f32_dpp v48, v48, v48 row_ror:1 row_mask:0xf bank_mask:0xf bound_ctrl:1
	ds_read_b128 v[152:155], v31 offset:15872
	ds_read_b128 v[156:159], v31 offset:19968
	v_pk_fma_f32 v[18:19], v[108:109], v[48:49], v[44:45] op_sel_hi:[1,0,1]
	v_pk_fma_f32 v[20:21], v[110:111], v[48:49], v[46:47] op_sel_hi:[1,0,1]
	s_waitcnt lgkmcnt(5)
	v_pk_mul_f32 v[42:43], v[134:135], v[20:21]
	v_pk_mul_f32 v[46:47], v[122:123], v[20:21]
	v_pk_fma_f32 v[42:43], v[132:133], v[18:19], v[42:43]
	v_pk_mul_f32 v[44:45], v[120:121], v[18:19]
	v_add_f32_e32 v48, v42, v43
	v_pk_fma_f32 v[44:45], v[124:125], v[176:177], v[44:45] op_sel:[0,1,0]
	v_pk_fma_f32 v[46:47], v[126:127], v[176:177], v[46:47] op_sel:[0,1,0]
	v_add_f32_dpp v48, v48, v48 row_ror:8 row_mask:0xf bank_mask:0xf bound_ctrl:1
	v_pk_mul_f32 v[50:51], v[116:117], v[18:19]
	v_pk_fma_f32 v[50:51], v[118:119], v[20:21], v[50:51]
	v_add_f32_dpp v48, v48, v48 row_ror:4 row_mask:0xf bank_mask:0xf bound_ctrl:1
	v_add_f32_e32 v192, v50, v51
	ds_read_b128 v[100:103], v31 offset:3840
	v_add_f32_dpp v48, v48, v48 row_ror:2 row_mask:0xf bank_mask:0xf bound_ctrl:1
	ds_read_b128 v[104:107], v31 offset:7936
	ds_read_b128 v[108:111], v31 offset:12032
	v_add_f32_dpp v48, v48, v48 row_ror:1 row_mask:0xf bank_mask:0xf bound_ctrl:1
	ds_read_b128 v[112:115], v31 offset:16128
	ds_read_b128 v[116:119], v31 offset:20224
	v_pk_fma_f32 v[18:19], v[128:129], v[48:49], v[44:45] op_sel_hi:[1,0,1]
	v_pk_fma_f32 v[20:21], v[130:131], v[48:49], v[46:47] op_sel_hi:[1,0,1]
	s_waitcnt lgkmcnt(5)
; DI u16 f2bf(float a) { return (u16)(pack2(a, 0.f) & 0xffffu); }
; DI void phase_scan(const Params& p, char* smem) {
;     ...
;       float2_t t2 = S01 * a01; t2 = S23 * a23 + t2;
;       const float2_t q01 = S01 * w01 + vv2 * k01, q23 = S23 * w23 + vv2 * k23;
;       float xs = t2.x + t2.y, ys = ypart;
;       xs += __builtin_bit_cast(float, __builtin_amdgcn_update_dpp(0, __builtin_bit_cast(int, xs), 0x128, 0xf, 0xf, false));
;       ys += __builtin_bit_cast(float, __builtin_amdgcn_update_dpp(0, __builtin_bit_cast(int, ys), 0x128, 0xf, 0xf, false));
;       xs += __builtin_bit_cast(float, __builtin_amdgcn_update_dpp(0, __builtin_bit_cast(int, xs), 0x124, 0xf, 0xf, false));
;       ys += __builtin_bit_cast(float, __builtin_amdgcn_update_dpp(0, __builtin_bit_cast(int, ys), 0x124, 0xf, 0xf, false));
;       xs += __builtin_bit_cast(float, __builtin_amdgcn_update_dpp(0, __builtin_bit_cast(int, xs), 0x122, 0xf, 0xf, false));
;       ys += __builtin_bit_cast(float, __builtin_amdgcn_update_dpp(0, __builtin_bit_cast(int, ys), 0x122, 0xf, 0xf, false));
;       xs += __builtin_bit_cast(float, __builtin_amdgcn_update_dpp(0, __builtin_bit_cast(int, xs), 0x121, 0xf, 0xf, false));
;       ys += __builtin_bit_cast(float, __builtin_amdgcn_update_dpp(0, __builtin_bit_cast(int, ys), 0x121, 0xf, 0xf, false));
;       if (s > 0) ysel = (kq == s - 1) ? ys : ysel;
;       const float2_t sa2 = {xs, xs};
;       S01 = sa2 * b01 + q01; S23 = sa2 * b23 + q23;
;       float2_t y2 = S01 * r01; y2 = S23 * r23 + y2;
;       ypart = y2.x + y2.y;
;     }
;     { const float yl = rowsum16(ypart); ysel = (kq == CH - 1) ? yl : ysel; }
;     Y[(size_t)(rowbase + rstep * kq) * 256 + h * 64 + vrow] = f2bf(ysel);
;     if (c + 1 < NCH) SCAN_LSTORE((c + 1) & 1);
	v_pk_mul_f32 v[42:43], v[154:155], v[20:21]
	v_pk_mul_f32 v[46:47], v[142:143], v[20:21]
	v_pk_fma_f32 v[42:43], v[152:153], v[18:19], v[42:43]
	v_pk_mul_f32 v[44:45], v[140:141], v[18:19]
	v_add_f32_e32 v48, v42, v43
	v_pk_fma_f32 v[44:45], v[144:145], v[178:179], v[44:45] op_sel_hi:[1,0,1]
	v_pk_fma_f32 v[46:47], v[146:147], v[178:179], v[46:47] op_sel_hi:[1,0,1]
	v_add_f32_dpp v48, v48, v48 row_ror:8 row_mask:0xf bank_mask:0xf bound_ctrl:1
	v_pk_mul_f32 v[50:51], v[136:137], v[18:19]
	v_pk_fma_f32 v[50:51], v[138:139], v[20:21], v[50:51]
	v_add_f32_dpp v48, v48, v48 row_ror:4 row_mask:0xf bank_mask:0xf bound_ctrl:1
	v_add_f32_e32 v193, v50, v51
	s_nop 0
	v_add_f32_dpp v48, v48, v48 row_ror:2 row_mask:0xf bank_mask:0xf bound_ctrl:1
	s_nop 1
	v_add_f32_dpp v48, v48, v48 row_ror:1 row_mask:0xf bank_mask:0xf bound_ctrl:1
	v_pk_fma_f32 v[18:19], v[148:149], v[48:49], v[44:45] op_sel_hi:[1,0,1]
	v_pk_fma_f32 v[20:21], v[150:151], v[48:49], v[46:47] op_sel_hi:[1,0,1]
	s_waitcnt lgkmcnt(0)
	v_pk_mul_f32 v[42:43], v[114:115], v[20:21]
	v_pk_mul_f32 v[46:47], v[102:103], v[20:21]
	v_pk_fma_f32 v[42:43], v[112:113], v[18:19], v[42:43]
	v_pk_mul_f32 v[44:45], v[100:101], v[18:19]
	v_add_f32_e32 v48, v42, v43
	v_pk_fma_f32 v[44:45], v[104:105], v[178:179], v[44:45] op_sel:[0,1,0]
	v_pk_fma_f32 v[46:47], v[106:107], v[178:179], v[46:47] op_sel:[0,1,0]
	v_add_f32_dpp v48, v48, v48 row_ror:8 row_mask:0xf bank_mask:0xf bound_ctrl:1
	v_pk_mul_f32 v[50:51], v[156:157], v[18:19]
	v_pk_fma_f32 v[50:51], v[158:159], v[20:21], v[50:51]
	v_add_f32_dpp v48, v48, v48 row_ror:4 row_mask:0xf bank_mask:0xf bound_ctrl:1
	v_add_f32_e32 v194, v50, v51
	s_nop 0
	v_add_f32_dpp v48, v48, v48 row_ror:2 row_mask:0xf bank_mask:0xf bound_ctrl:1
	s_nop 1
	v_add_f32_dpp v48, v48, v48 row_ror:1 row_mask:0xf bank_mask:0xf bound_ctrl:1
	v_pk_fma_f32 v[18:19], v[108:109], v[48:49], v[44:45] op_sel_hi:[1,0,1]
	v_pk_fma_f32 v[20:21], v[110:111], v[48:49], v[46:47] op_sel_hi:[1,0,1]
	v_pk_mul_f32 v[50:51], v[116:117], v[18:19]
	v_pk_fma_f32 v[50:51], v[118:119], v[20:21], v[50:51]
	v_add_f32_e32 v195, v50, v51
	v_add_f32_dpp v60, v180, v180 row_ror:8 row_mask:0xf bank_mask:0x3 bound_ctrl:1
	v_add_f32_dpp v61, v181, v181 row_ror:8 row_mask:0xf bank_mask:0x3 bound_ctrl:1
	v_add_f32_dpp v62, v182, v182 row_ror:8 row_mask:0xf bank_mask:0x3 bound_ctrl:1
	v_add_f32_dpp v63, v183, v183 row_ror:8 row_mask:0xf bank_mask:0x3 bound_ctrl:1
	v_add_f32_dpp v64, v184, v184 row_ror:8 row_mask:0xf bank_mask:0x3 bound_ctrl:1
	v_add_f32_dpp v65, v185, v185 row_ror:8 row_mask:0xf bank_mask:0x3 bound_ctrl:1
	v_add_f32_dpp v66, v186, v186 row_ror:8 row_mask:0xf bank_mask:0x3 bound_ctrl:1
	v_add_f32_dpp v67, v187, v187 row_ror:8 row_mask:0xf bank_mask:0x3 bound_ctrl:1
	v_add_f32_dpp v60, v188, v188 row_ror:8 row_mask:0xf bank_mask:0xc bound_ctrl:1
	v_add_f32_dpp v61, v189, v189 row_ror:8 row_mask:0xf bank_mask:0xc bound_ctrl:1
	v_add_f32_dpp v62, v190, v190 row_ror:8 row_mask:0xf bank_mask:0xc bound_ctrl:1
	v_add_f32_dpp v63, v191, v191 row_ror:8 row_mask:0xf bank_mask:0xc bound_ctrl:1
	v_add_f32_dpp v64, v192, v192 row_ror:8 row_mask:0xf bank_mask:0xc bound_ctrl:1
	v_add_f32_dpp v65, v193, v193 row_ror:8 row_mask:0xf bank_mask:0xc bound_ctrl:1
	v_add_f32_dpp v66, v194, v194 row_ror:8 row_mask:0xf bank_mask:0xc bound_ctrl:1
	v_add_f32_dpp v67, v195, v195 row_ror:8 row_mask:0xf bank_mask:0xc bound_ctrl:1
	v_add_f32_dpp v68, v60, v60 row_half_mirror row_mask:0xf bank_mask:0x5 bound_ctrl:1
	v_add_f32_dpp v69, v61, v61 row_half_mirror row_mask:0xf bank_mask:0x5 bound_ctrl:1
	v_add_f32_dpp v70, v62, v62 row_half_mirror row_mask:0xf bank_mask:0x5 bound_ctrl:1
	v_add_f32_dpp v71, v63, v63 row_half_mirror row_mask:0xf bank_mask:0x5 bound_ctrl:1
	v_add_f32_dpp v68, v64, v64 row_half_mirror row_mask:0xf bank_mask:0xa bound_ctrl:1
	v_add_f32_dpp v69, v65, v65 row_half_mirror row_mask:0xf bank_mask:0xa bound_ctrl:1
	v_add_f32_dpp v70, v66, v66 row_half_mirror row_mask:0xf bank_mask:0xa bound_ctrl:1
	v_add_f32_dpp v71, v67, v67 row_half_mirror row_mask:0xf bank_mask:0xa bound_ctrl:1
	v_cndmask_b32_e64 v52, v70, v68, s[8:9]
	v_cndmask_b32_e64 v53, v68, v70, s[8:9]
	v_cndmask_b32_e64 v54, v71, v69, s[8:9]
	v_cndmask_b32_e64 v55, v69, v71, s[8:9]
	v_add_f32_dpp v72, v52, v53 quad_perm:[3,2,1,0] row_mask:0xf bank_mask:0xf bound_ctrl:1
	v_add_f32_dpp v73, v54, v55 quad_perm:[3,2,1,0] row_mask:0xf bank_mask:0xf bound_ctrl:1
	v_cndmask_b32_e64 v52, v73, v72, s[10:11]
	v_cndmask_b32_e64 v53, v72, v73, s[10:11]
	s_nop 1
	v_add_f32_dpp v31, v52, v53 quad_perm:[1,0,3,2] row_mask:0xf bank_mask:0xf bound_ctrl:1
	v_cvt_pk_bf16_f32 v32, v31, s0
	v_ashrrev_i32_e32 v31, 31, v30
	v_lshlrev_b64 v[30:31], 9, v[30:31]
	v_lshl_add_u64 v[30:31], v[16:17], 0, v[30:31]
	flat_store_short v[30:31], v32
	s_cbranch_vccnz .LBB0_507
	s_bitcmp1_b32 s96, 0
	s_cselect_b32 s46, 0x5400, 0
	s_waitcnt vmcnt(0)
	v_lshlrev_b32_e32 v30, 16, v4
	v_and_b32_e32 v31, 0xffff0000, v4
	v_lshlrev_b32_e32 v32, 16, v5
	v_and_b32_e32 v33, 0xffff0000, v5
	v_add_u32_e32 v34, s46, v26
	v_pk_add_f32 v[30:31], v[30:31], 1.0 op_sel_hi:[1,0] neg_lo:[1,0] neg_hi:[1,0]
	v_pk_add_f32 v[32:33], v[32:33], 1.0 op_sel_hi:[1,0] neg_lo:[1,0] neg_hi:[1,0]
	ds_write_b128 v34, v[30:33]
	v_lshlrev_b32_e32 v30, 16, v6
	v_and_b32_e32 v31, 0xffff0000, v6
	v_lshlrev_b32_e32 v32, 16, v7
	v_and_b32_e32 v33, 0xffff0000, v7
	ds_write_b128 v34, v[30:33] offset:4096
	v_lshlrev_b32_e32 v30, 16, v8
	v_and_b32_e32 v31, 0xffff0000, v8
	v_lshlrev_b32_e32 v32, 16, v9
	v_and_b32_e32 v33, 0xffff0000, v9
	ds_write_b128 v34, v[30:33] offset:8192
	v_lshlrev_b32_e32 v30, 16, v10
	v_and_b32_e32 v31, 0xffff0000, v10
	v_lshlrev_b32_e32 v32, 16, v11
	v_and_b32_e32 v33, 0xffff0000, v11
	ds_write_b128 v34, v[30:33] offset:12288
	v_lshlrev_b32_e32 v30, 16, v12
	v_and_b32_e32 v31, 0xffff0000, v12
	v_lshlrev_b32_e32 v32, 16, v13
	v_and_b32_e32 v33, 0xffff0000, v13
	ds_write_b128 v34, v[30:33] offset:16384
	v_lshlrev_b32_e32 v30, 16, v27
	v_add_u32_e32 v31, s46, v28
	ds_write_b32 v31, v30 offset:20480
	s_branch .LBB0_507

; DI void attn_item(const Params& p, int item, char* smem) {
;     ...
;   for (int kt = 0; kt < nkt; kt += 2) {
;     if (kt + 2 < nkt) gload(b, kt + 2);
;     tile_compute(0);
;     lstore(a, 1);
;     __syncthreads();
;     if (kt + 3 < nkt) gload(a, kt + 3);
;     tile_compute(1);
;     if (kt + 2 < nkt) lstore(b, 0);
;     __syncthreads();
;   }
.LBB0_539:
	v_add_u32_e32 v140, s50, v140
	v_add_u32_e32 v142, s66, v142
	v_add_u32_e32 v144, s66, v144
	s_andn2_b64 vcc, exec, s[4:5]
	v_add_u32_e32 v146, s66, v146
	s_waitcnt lgkmcnt(0)
	s_barrier
	s_cbranch_vccz .LBB0_518
	s_mov_b32 s12, s11
	s_branch .LBB0_529
